# XCD-local barriers after the resid-out / rmsnorm / gate-up / down phases (consumers read only rows produced in their own XCD; rmsnorm remapped to XCD-local rows; placement checked at start-up, full ba
# speedup vs baseline: 1.0133x; 1.0133x over previous
.LBB0_14:
	s_load_dwordx16 s[4:19], s[0:1], 0x0
	v_cmp_eq_u32_e64 s[34:35], 0, v163
	v_cmp_ne_u32_e32 vcc, 0, v163
	s_waitcnt lgkmcnt(0)
	v_writelane_b32 v237, s4, 1
	s_nop 1
	v_writelane_b32 v237, s5, 2
	v_writelane_b32 v237, s6, 3
	v_writelane_b32 v237, s7, 4
	v_writelane_b32 v237, s8, 5
	v_writelane_b32 v237, s9, 6
	v_writelane_b32 v237, s10, 7
	v_writelane_b32 v237, s11, 8
	v_writelane_b32 v237, s12, 9
	v_writelane_b32 v237, s13, 10
	v_writelane_b32 v237, s14, 11
	v_writelane_b32 v237, s15, 12
	v_writelane_b32 v237, s16, 13
	v_writelane_b32 v237, s17, 14
	v_writelane_b32 v237, s18, 15
	v_writelane_b32 v237, s19, 16
	s_load_dwordx16 s[4:19], s[0:1], 0x40
	s_waitcnt lgkmcnt(0)
	v_writelane_b32 v237, s4, 17
	s_nop 1
	v_writelane_b32 v237, s5, 18
	v_writelane_b32 v237, s6, 19
	v_writelane_b32 v237, s7, 20
	v_writelane_b32 v237, s8, 21
	v_writelane_b32 v237, s9, 22
	v_writelane_b32 v237, s10, 23
	v_writelane_b32 v237, s11, 24
	v_writelane_b32 v237, s12, 25
	v_writelane_b32 v237, s13, 26
	v_writelane_b32 v237, s14, 27
	v_writelane_b32 v237, s15, 28
	v_writelane_b32 v237, s16, 29
	v_writelane_b32 v237, s17, 30
	v_writelane_b32 v237, s18, 31
	v_writelane_b32 v237, s19, 32
	s_load_dwordx16 s[4:19], s[0:1], 0x80
	s_waitcnt lgkmcnt(0)
	v_writelane_b32 v237, s4, 33
	s_nop 1
	v_writelane_b32 v237, s5, 34
	v_writelane_b32 v237, s6, 35
	v_writelane_b32 v237, s7, 36
	v_writelane_b32 v237, s8, 37
	v_writelane_b32 v237, s9, 38
	v_writelane_b32 v237, s10, 39
	v_writelane_b32 v237, s11, 40
	v_writelane_b32 v237, s12, 41
	v_writelane_b32 v237, s13, 42
	v_writelane_b32 v237, s14, 43
	v_writelane_b32 v237, s15, 44
	v_writelane_b32 v237, s16, 45
	v_writelane_b32 v237, s17, 46
	v_writelane_b32 v237, s18, 47
	v_writelane_b32 v237, s19, 48
	s_load_dwordx16 s[76:91], s[0:1], 0x100
	s_load_dwordx8 s[4:11], s[0:1], 0x140
	s_getreg_b32 s2, hwreg(HW_REG_XCC_ID, 0, 4)
	s_and_b32 s20, s2, 15
	s_waitcnt lgkmcnt(0)
	v_writelane_b32 v237, s4, 49
	s_nop 1
	v_writelane_b32 v237, s5, 50
	v_writelane_b32 v237, s6, 51
	v_writelane_b32 v237, s7, 52
	v_writelane_b32 v237, s8, 53
	v_writelane_b32 v237, s9, 54
	v_writelane_b32 v237, s10, 55
	v_writelane_b32 v237, s11, 56
	s_load_dwordx8 s[4:11], s[0:1], 0x168
	s_waitcnt lgkmcnt(0)
	v_writelane_b32 v237, s4, 57
	s_nop 1
	v_writelane_b32 v237, s5, 58
	v_writelane_b32 v237, s6, 59
	v_writelane_b32 v237, s7, 60
	v_writelane_b32 v237, s8, 61
	v_writelane_b32 v237, s9, 62
	v_writelane_b32 v236, s11, 0
	s_mov_b32 s5, 0
	v_writelane_b32 v237, s10, 63
	s_and_saveexec_b64 s[2:3], vcc
	s_xor_b64 s[2:3], exec, s[2:3]
	s_add_u32 s6, s0, 0x188
	s_addc_u32 s7, s1, 0
	s_lshl_b32 s4, s20, 6
	s_or_saveexec_b64 s[2:3], s[2:3]
	v_mov_b32_e32 v162, 1
	v_mov_b64_e32 v[164:165], s[6:7]
	v_mov_b64_e32 v[0:1], s[4:5]
	v_mov_b32_e32 v166, 1
	s_xor_b64 exec, exec, s[2:3]
	s_cbranch_execz .LBB0_33
	s_mov_b64 s[6:7], exec
	v_mbcnt_lo_u32_b32 v0, s6, 0
	v_mbcnt_hi_u32_b32 v0, s7, v0
	s_lshl_b32 s4, s20, 6
	s_mov_b32 s5, 0
	v_cmp_eq_u32_e32 vcc, 0, v0
	s_and_saveexec_b64 s[8:9], vcc
	s_cbranch_execz .LBB0_19
	s_load_dwordx8 s[12:19], s[0:1], 0x168
	s_lshl_b32 s10, s4, 2
	s_bcnt1_i32_b64 s6, s[6:7]
	v_mov_b32_e32 v0, s10
	v_mov_b32_e32 v1, s6
	s_waitcnt lgkmcnt(0)
	global_atomic_add v0, v1, s[16:17] offset:1024
	v_readlane_b32 s10, v237, 0
	s_and_b32 s10, s10, 7
	s_lshl_b32 s10, s10, 2
	s_add_u32 s10, s10, 0x3700
	v_mov_b32_e32 v2, s10
	s_lshl_b32 s10, 1, s20
	v_mov_b32_e32 v3, s10
	global_atomic_or v2, v3, s[16:17]

.LBB0_33:
	s_or_b64 exec, exec, s[2:3]
	s_add_u32 s0, s78, 0x1a00
	s_addc_u32 s1, s79, 0
	v_writelane_b32 v236, s0, 1
	v_sub_u32_e32 v2, 0, v166
	s_mov_b32 s41, 0
	v_writelane_b32 v236, s1, 2
	v_readlane_b32 s0, v237, 57
	v_readlane_b32 s4, v237, 61
	v_readlane_b32 s5, v237, 62
	s_add_u32 s0, s4, 0x3840
	v_readlane_b32 s1, v237, 58
	v_readlane_b32 s7, v236, 0
	v_writelane_b32 v236, s0, 3
	s_addc_u32 s0, s5, 0
	v_writelane_b32 v236, s0, 4
	v_lshl_add_u64 v[0:1], v[0:1], 2, s[4:5]
	s_mov_b64 s[0:1], 0x1400
	v_lshl_add_u64 v[168:169], v[0:1], 0, s[0:1]
	s_mov_b64 s[0:1], 0x2400
	v_lshl_add_u64 v[170:171], v[0:1], 0, s[0:1]
	s_add_u32 s0, s4, 0x200
	s_addc_u32 s1, s5, 0
	v_writelane_b32 v236, s0, 5
	v_cvt_f32_u32_e32 v0, v166
	v_cvt_f32_u32_e32 v1, v162
	v_writelane_b32 v236, s1, 6
	s_add_u32 s0, s4, 0x3400
	s_addc_u32 s1, s5, 0
	v_writelane_b32 v236, s0, 7
	v_rcp_iflag_f32_e32 v0, v0
	v_rcp_iflag_f32_e32 v1, v1
	v_writelane_b32 v236, s1, 8
	s_add_u32 s0, s4, 0x3500
	s_addc_u32 s1, s5, 0
	v_writelane_b32 v236, s0, 9
	v_mul_f32_e32 v0, 0x4f7ffffe, v0
	v_cvt_u32_f32_e32 v0, v0
	v_writelane_b32 v236, s1, 10
	s_mov_b64 s[0:1], 0
	v_writelane_b32 v236, s0, 11
	v_mul_f32_e32 v1, 0x4f7ffffe, v1
	v_cvt_u32_f32_e32 v3, v1
	v_writelane_b32 v236, s1, 12
	v_writelane_b32 v236, s44, 13
	v_mul_lo_u32 v2, v2, v0
	v_mul_hi_u32 v2, v0, v2
	v_writelane_b32 v236, s45, 14
	v_writelane_b32 v236, s46, 15
	v_writelane_b32 v236, s47, 16
	v_writelane_b32 v236, s48, 17
	v_writelane_b32 v236, s49, 18
	v_writelane_b32 v236, s50, 19
	v_writelane_b32 v236, s51, 20
	v_writelane_b32 v236, s52, 21
	v_writelane_b32 v236, s53, 22
	v_writelane_b32 v236, s54, 23
	v_writelane_b32 v236, s55, 24
	v_writelane_b32 v236, s56, 25
	v_writelane_b32 v236, s57, 26
	v_writelane_b32 v236, s58, 27
	v_writelane_b32 v236, s59, 28
	v_writelane_b32 v236, s76, 29
	v_add_u32_e32 v172, v0, v2
	v_sub_u32_e32 v0, 0, v162
	v_writelane_b32 v236, s77, 30
	v_writelane_b32 v236, s78, 31
	v_writelane_b32 v236, s79, 32
	v_writelane_b32 v236, s80, 33
	v_writelane_b32 v236, s81, 34
	v_writelane_b32 v236, s82, 35
	v_writelane_b32 v236, s83, 36
	v_writelane_b32 v236, s84, 37
	v_writelane_b32 v236, s85, 38
	v_writelane_b32 v236, s86, 39
	v_writelane_b32 v236, s87, 40
	v_mul_lo_u32 v0, v0, v3
	v_writelane_b32 v236, s88, 41
	v_mul_hi_u32 v0, v3, v0
	v_writelane_b32 v236, s89, 42
	v_add_u32_e32 v174, v3, v0
	v_writelane_b32 v236, s90, 43
	v_readlane_b32 s6, v237, 63
	v_mbcnt_lo_u32_b32 v0, -1, 0
	v_writelane_b32 v236, s91, 44
	v_mov_b32_e32 v1, 0
	s_movk_i32 s33, 0x70
	s_movk_i32 s36, 0x3ff
	s_mov_b32 s37, 0x5a000
	s_movk_i32 s38, 0x1680
	s_mov_b32 s39, 0x2d000
	s_mov_b32 s42, 0x87000
	s_movk_i32 s43, 0x880
	v_mov_b32_e32 v167, 0x358637bd
	s_movk_i32 s92, 0x480
	s_movk_i32 s93, 0x3300
	v_mov_b32_e32 v173, 0x3c0881c4
	v_mov_b32_e32 v175, 0xbab64f3b
	s_movk_i32 s94, 0x2080
	s_movk_i32 s95, 0x3000
	v_mov_b32_e32 v192, 1
	v_mbcnt_hi_u32_b32 v193, -1, v0
	v_mov_b32_e32 v194, 0x7f800000
	v_not_b32_e32 v195, 63
	v_not_b32_e32 v196, 31
	v_mov_b32_e32 v197, 0x7fc00000
	v_mov_b32_e32 v198, 0x3300
	v_mov_b32_e32 v176, 0xfe00
	v_mov_b32_e32 v199, 0xf149f2ca
	v_mov_b32_e32 v200, 0x6080
	v_mov_b32_e32 v201, 0xff800000
	v_mov_b32_e32 v202, 0x461c4000
	v_mov_b32_e32 v203, 0xb00
	v_mov_b32_e32 v204, 0x200
	v_mov_b32_e32 v205, 0x100
	v_mov_b64_e32 v[178:179], 0x3460
	v_mov_b64_e32 v[180:181], 0x3400
	s_mov_b32 s6, s41
	v_writelane_b32 v234, s41, 22
	v_writelane_b32 v234, s41, 24
	v_writelane_b32 v234, s41, 25
	v_writelane_b32 v234, s41, 23
	v_readfirstlane_b32 s0, v164
	v_readfirstlane_b32 s1, v165
	s_nop 4
	s_load_dword s0, s[0:1], 0x0
	s_waitcnt lgkmcnt(0)
	v_writelane_b32 v234, s0, 21
	v_writelane_b32 v236, s34, 45
	v_readlane_b32 s2, v237, 59
	v_readlane_b32 s3, v237, 60
	v_writelane_b32 v236, s35, 46
	s_branch .LBB0_35

.LBB0_38:
	v_readlane_b32 s0, v234, 25
	s_cmp_lg_u32 s0, 0
	s_cbranch_scc1 .Lxl_known
	v_readlane_b32 s0, v237, 61
	v_readlane_b32 s1, v237, 62
	v_mov_b32_e32 v0, 0x3700
	s_nop 3
	global_load_dwordx4 v[2:5], v0, s[0:1] sc1
	global_load_dwordx4 v[6:9], v0, s[0:1] offset:16 sc1
	s_mov_b32 s4, 0
	s_mov_b32 s5, 0
	s_waitcnt vmcnt(0)
	v_readfirstlane_b32 s0, v2
	s_add_i32 s1, s0, -1
	s_and_b32 s1, s1, s0
	s_or_b32 s4, s4, s1
	s_cmp_eq_u32 s0, 0
	s_cselect_b32 s1, 1, 0
	s_or_b32 s4, s4, s1
	s_or_b32 s5, s5, s0
	v_readfirstlane_b32 s0, v3
	s_add_i32 s1, s0, -1
	s_and_b32 s1, s1, s0
	s_or_b32 s4, s4, s1
	s_cmp_eq_u32 s0, 0
	s_cselect_b32 s1, 1, 0
	s_or_b32 s4, s4, s1
	s_or_b32 s5, s5, s0
	v_readfirstlane_b32 s0, v4
	s_add_i32 s1, s0, -1
	s_and_b32 s1, s1, s0
	s_or_b32 s4, s4, s1
	s_cmp_eq_u32 s0, 0
	s_cselect_b32 s1, 1, 0
	s_or_b32 s4, s4, s1
	s_or_b32 s5, s5, s0
	v_readfirstlane_b32 s0, v5
	s_add_i32 s1, s0, -1
	s_and_b32 s1, s1, s0
	s_or_b32 s4, s4, s1
	s_cmp_eq_u32 s0, 0
	s_cselect_b32 s1, 1, 0
	s_or_b32 s4, s4, s1
	s_or_b32 s5, s5, s0
	v_readfirstlane_b32 s0, v6
	s_add_i32 s1, s0, -1
	s_and_b32 s1, s1, s0
	s_or_b32 s4, s4, s1
	s_cmp_eq_u32 s0, 0
	s_cselect_b32 s1, 1, 0
	s_or_b32 s4, s4, s1
	s_or_b32 s5, s5, s0
	v_readfirstlane_b32 s0, v7
	s_add_i32 s1, s0, -1
	s_and_b32 s1, s1, s0
	s_or_b32 s4, s4, s1
	s_cmp_eq_u32 s0, 0
	s_cselect_b32 s1, 1, 0
	s_or_b32 s4, s4, s1
	s_or_b32 s5, s5, s0
	v_readfirstlane_b32 s0, v8
	s_add_i32 s1, s0, -1
	s_and_b32 s1, s1, s0
	s_or_b32 s4, s4, s1
	s_cmp_eq_u32 s0, 0
	s_cselect_b32 s1, 1, 0
	s_or_b32 s4, s4, s1
	s_or_b32 s5, s5, s0
	v_readfirstlane_b32 s0, v9
	s_add_i32 s1, s0, -1
	s_and_b32 s1, s1, s0
	s_or_b32 s4, s4, s1
	s_cmp_eq_u32 s0, 0
	s_cselect_b32 s1, 1, 0
	s_or_b32 s4, s4, s1
	s_or_b32 s5, s5, s0
	s_xor_b32 s5, s5, 0xff
	s_or_b32 s4, s4, s5
	s_cmp_eq_u32 s4, 0
	s_cselect_b32 s0, 1, 2
	v_writelane_b32 v234, s0, 25

.LBB0_69:
	s_andn2_b64 vcc, exec, s[0:1]
	s_cbranch_vccnz .LBB0_74
	v_and_b32_e32 v185, 63, v163
	v_lshlrev_b32_e32 v182, 4, v185
	v_lshlrev_b32_e32 v183, 3, v185
	v_xor_b32_e32 v184, 32, v185
	v_lshlrev_b32_e32 v184, 2, v184
	v_lshrrev_b32_e32 v186, 6, v163
	v_readlane_b32 s2, v236, 47
	v_readlane_b32 s3, v236, 48
	global_load_dword v185, v[164:165], off
	s_nop 3
	global_load_dwordx4 v[130:133], v182, s[2:3] offset:0
	global_load_dwordx4 v[134:137], v182, s[2:3] offset:1024
	global_load_dwordx4 v[138:141], v182, s[2:3] offset:2048
	global_load_dwordx4 v[142:145], v182, s[2:3] offset:3072
	v_readlane_b32 s2, v237, 0
	v_readfirstlane_b32 s3, v186
	s_and_b32 s4, s2, 7
	s_lshl_b32 s4, s4, 11
	s_lshr_b32 s2, s2, 3
	s_lshl_b32 s2, s2, 2
	s_add_i32 s2, s2, s3
	s_add_i32 s2, s2, s4
	s_waitcnt vmcnt(4)
	s_movk_i32 s3, 0x100

.Lr8_stp7:
.Lr8_next:
.LBB0_74:
	s_mov_b64 s[0:1], 0

.LBB0_523:
	s_or_b64 exec, exec, s[2:3]
	v_and_b32_e32 v185, 63, v163
	v_lshlrev_b32_e32 v182, 4, v185
	v_lshlrev_b32_e32 v183, 3, v185
	v_xor_b32_e32 v184, 32, v185
	v_lshlrev_b32_e32 v184, 2, v184
	v_lshrrev_b32_e32 v186, 6, v163
	v_readlane_b32 s2, v235, 26
	v_readlane_b32 s3, v235, 27
	global_load_dword v185, v[164:165], off
	s_nop 3
	global_load_dwordx4 v[130:133], v182, s[2:3] offset:0
	global_load_dwordx4 v[134:137], v182, s[2:3] offset:1024
	global_load_dwordx4 v[138:141], v182, s[2:3] offset:2048
	global_load_dwordx4 v[142:145], v182, s[2:3] offset:3072
	v_readlane_b32 s2, v237, 0
	v_readfirstlane_b32 s3, v186
	s_and_b32 s4, s2, 7
	s_lshl_b32 s4, s4, 11
	s_lshr_b32 s2, s2, 3
	s_lshl_b32 s2, s2, 2
	s_add_i32 s2, s2, s3
	s_add_i32 s2, s2, s4
	s_waitcnt vmcnt(4)
	s_movk_i32 s3, 0x100

.Lr0_stp7:
.Lr0_next:
.LBB0_529:
	s_mov_b64 s[0:1], -1

.LBB0_547:
	s_andn2_saveexec_b64 s[2:3], s[2:3]
	s_cbranch_execz .LBB0_37
	s_mov_b64 s[2:3], exec
	v_readlane_b32 s4, v234, 25
	s_cmp_eq_u32 s4, 1
	s_cbranch_scc0 .Lxl_full
	v_readlane_b32 s4, v235, 32
	s_cmp_lt_u32 s4, 7
	s_cbranch_scc0 .LBB0_36
.Lxl_full:
	buffer_wbl2 sc1
	s_waitcnt vmcnt(0)
	v_mbcnt_lo_u32_b32 v0, s2, 0
	v_mbcnt_hi_u32_b32 v0, s3, v0
	v_cmp_eq_u32_e32 vcc, 0, v0
	s_and_saveexec_b64 s[4:5], vcc
	s_cbranch_execz .LBB0_550
	s_bcnt1_i32_b64 s2, s[2:3]
	v_mov_b32_e32 v2, s2
	v_readlane_b32 s2, v236, 7
	v_readlane_b32 s3, v236, 8
	s_nop 4
	global_atomic_add v2, v1, v2, s[2:3] sc0
